# P0 weight conversion: the 16 gain vectors of a tile loaded together (was 2 loads + vmcnt(1)/vmcnt(0) per 8 columns)
# baseline (speedup 1.0000x reference)
; __device__ __forceinline__ void cvt_job(int& tbase, const float* __restrict__ src, int Nsrc, int K, bf16_t* __restrict__ dst, int ndst, int mode,
;                                         const float* __restrict__ gain, const float* __restrict__ up_f, const float* __restrict__ up_b, int bi, int nb) {
;     ...
;     int t0 = (gw - tbase % nw + nw) % nw; tbase += ntile;
;     for (int t = t0; t < ntile; t += nw) {
;         const int n0 = (t % nT) << 6, k0 = (t / nT) << 6, n = n0 + lane;
;         int col = n; float scale = 1.f;
;         if (mode == CM_SWIGLU) { const int j = n & 255, pn = n >> 8; col = (j < 128) ? pn * 128 + j : FF + pn * 128 + (j - 128); }
;         else if (mode == CM_WIN_A) { scale = (n < 512) ? 0.08838834764831845f : 1.f; }
;         else if (mode == CM_WIN_B) { col = 3104 + n; }
;         float v[64];
;         if (mode == CM_FOLD) {
;             const int dirb = n >> 9, c = n & 511; const float* up = dirb ? up_b : up_f;
;             float upv[16];
; #pragma unroll
;             for (int r = 0; r < 16; ++r) upv[r] = up[r * 512 + c];
; #pragma unroll
;             for (int j = 0; j < 64; ++j) { const float* wp = src + (size_t)(k0 + j) * Nsrc + 3072 + 16 * dirb; float sacc = 0.f;
; #pragma unroll
;                 for (int r = 0; r < 16; ++r) sacc += wp[r] * upv[r];
;                 v[j] = sacc; }
;         } else {
;             const float* sp = src + (size_t)k0 * Nsrc + col;
; #pragma unroll
;             for (int j = 0; j < 64; ++j) v[j] = sp[(size_t)j * Nsrc];
.LBB0_25:
	s_mov_b32 s20, 0x2e8ba2e9
	v_mul_hi_i32 v0, v9, s20
	v_lshrrev_b32_e32 v1, 31, v0
	v_ashrrev_i32_e32 v0, 4, v0
	v_add_u32_e32 v1, v0, v1
	s_movk_i32 s20, 0xea00
	v_mad_u64_u32 v[2:3], s[20:21], v1, s20, v[8:9]
	v_and_b32_e32 v3, 0xff, v2
	s_movk_i32 s20, 0x80
	v_cmp_gt_u32_e32 vcc, s20, v3
	s_movk_i32 s20, 0xf500
	s_waitcnt vmcnt(62)
	v_mad_u64_u32 v[4:5], s[20:21], v1, s20, v[10:11]
	v_lshlrev_b32_e32 v0, 6, v1
	v_and_b32_e32 v1, 0xffffff80, v4
	s_movk_i32 s20, 0xa80
	v_add3_u32 v4, v1, v3, s20
	v_or_b32_e32 v1, v3, v1
	v_cndmask_b32_e32 v4, v4, v1, vcc
	s_movk_i32 s20, 0x5800
	v_mad_i64_i32 v[6:7], s[20:21], v0, s20, v[12:13]
	v_ashrrev_i32_e32 v5, 31, v4
	v_lshl_add_u64 v[4:5], v[4:5], 2, v[6:7]
	s_movk_i32 s20, 0x5000
	v_add_co_u32_e32 v6, vcc, s20, v4
	s_mov_b32 s20, 0xb000
	s_nop 0
	v_addc_co_u32_e32 v7, vcc, 0, v5, vcc
	global_load_dword v16, v[6:7], off offset:2048
	v_add_co_u32_e32 v6, vcc, s20, v4
	s_mov_b32 s20, 0x10000
	s_nop 0
	v_addc_co_u32_e32 v7, vcc, 0, v5, vcc
	global_load_dword v11, v[4:5], off
	global_load_dword v17, v[6:7], off
	v_add_co_u32_e32 v6, vcc, s20, v4
	s_mov_b32 s20, 0x16000
	s_nop 0
	v_addc_co_u32_e32 v7, vcc, 0, v5, vcc
	global_load_dword v18, v[6:7], off offset:2048
	v_add_co_u32_e32 v6, vcc, s20, v4
	s_mov_b32 s20, 0x1b000
	s_nop 0
	v_addc_co_u32_e32 v7, vcc, 0, v5, vcc
	global_load_dword v19, v[6:7], off
	v_add_co_u32_e32 v6, vcc, s20, v4
	s_mov_b32 s20, 0x21000
	s_nop 0
	v_addc_co_u32_e32 v7, vcc, 0, v5, vcc
	global_load_dword v20, v[6:7], off offset:2048
	v_add_co_u32_e32 v6, vcc, s20, v4
	s_mov_b32 s20, 0x26000
	s_nop 0
	v_addc_co_u32_e32 v7, vcc, 0, v5, vcc
	global_load_dword v21, v[6:7], off
	v_add_co_u32_e32 v6, vcc, s20, v4
	s_mov_b32 s20, 0x2c000
	s_nop 0
	v_addc_co_u32_e32 v7, vcc, 0, v5, vcc
	global_load_dword v23, v[6:7], off offset:2048
	v_add_co_u32_e32 v6, vcc, s20, v4
	s_mov_b32 s20, 0x31000
	s_nop 0
	v_addc_co_u32_e32 v7, vcc, 0, v5, vcc
	global_load_dword v22, v[6:7], off
	v_add_co_u32_e32 v6, vcc, s20, v4
	s_mov_b32 s20, 0x37000
	s_nop 0
	v_addc_co_u32_e32 v7, vcc, 0, v5, vcc
	global_load_dword v24, v[6:7], off offset:2048
	v_add_co_u32_e32 v6, vcc, s20, v4
	s_mov_b32 s20, 0x3c000
	s_nop 0
	v_addc_co_u32_e32 v7, vcc, 0, v5, vcc
	global_load_dword v25, v[6:7], off
	v_add_co_u32_e32 v6, vcc, s20, v4
	s_mov_b32 s20, 0x42000
	s_nop 0
	v_addc_co_u32_e32 v7, vcc, 0, v5, vcc
	global_load_dword v26, v[6:7], off offset:2048
	v_add_co_u32_e32 v6, vcc, s20, v4
	s_mov_b32 s20, 0x47000
	s_nop 0
	v_addc_co_u32_e32 v7, vcc, 0, v5, vcc
	global_load_dword v27, v[6:7], off
	v_add_co_u32_e32 v6, vcc, s20, v4
	s_mov_b32 s20, 0x4d000
	s_nop 0
	v_addc_co_u32_e32 v7, vcc, 0, v5, vcc
	global_load_dword v28, v[6:7], off offset:2048
	v_add_co_u32_e32 v6, vcc, s20, v4
	s_mov_b32 s20, 0x52000
	s_nop 0
	v_addc_co_u32_e32 v7, vcc, 0, v5, vcc
	global_load_dword v29, v[6:7], off
	v_add_co_u32_e32 v6, vcc, s20, v4
	s_mov_b32 s20, 0x58000
	s_nop 0
	v_addc_co_u32_e32 v7, vcc, 0, v5, vcc
	global_load_dword v31, v[6:7], off offset:2048
	v_add_co_u32_e32 v6, vcc, s20, v4
	s_mov_b32 s20, 0x5d000
	s_nop 0
	v_addc_co_u32_e32 v7, vcc, 0, v5, vcc
	global_load_dword v30, v[6:7], off
	v_add_co_u32_e32 v6, vcc, s20, v4
	s_mov_b32 s20, 0x63000
	s_nop 0
	v_addc_co_u32_e32 v7, vcc, 0, v5, vcc
	global_load_dword v32, v[6:7], off offset:2048
	v_add_co_u32_e32 v6, vcc, s20, v4
	s_mov_b32 s20, 0x68000
	s_nop 0
	v_addc_co_u32_e32 v7, vcc, 0, v5, vcc
	global_load_dword v33, v[6:7], off
	v_add_co_u32_e32 v6, vcc, s20, v4
	s_mov_b32 s20, 0x6e000
	s_nop 0
	v_addc_co_u32_e32 v7, vcc, 0, v5, vcc
	global_load_dword v34, v[6:7], off offset:2048
	v_add_co_u32_e32 v6, vcc, s20, v4
	s_mov_b32 s20, 0x73000
	s_nop 0
	v_addc_co_u32_e32 v7, vcc, 0, v5, vcc
	global_load_dword v35, v[6:7], off
	v_add_co_u32_e32 v6, vcc, s20, v4
	s_mov_b32 s20, 0x79000
	s_nop 0
	v_addc_co_u32_e32 v7, vcc, 0, v5, vcc
	global_load_dword v36, v[6:7], off offset:2048
	v_add_co_u32_e32 v6, vcc, s20, v4
	s_mov_b32 s20, 0x7e000
	s_nop 0
	v_addc_co_u32_e32 v7, vcc, 0, v5, vcc
	global_load_dword v37, v[6:7], off
	v_add_co_u32_e32 v6, vcc, s20, v4
	s_mov_b32 s20, 0x84000
	s_nop 0
	v_addc_co_u32_e32 v7, vcc, 0, v5, vcc
	global_load_dword v39, v[6:7], off offset:2048
	v_add_co_u32_e32 v6, vcc, s20, v4
	s_mov_b32 s20, 0x89000
	s_nop 0
	v_addc_co_u32_e32 v7, vcc, 0, v5, vcc
	global_load_dword v38, v[6:7], off
	v_add_co_u32_e32 v6, vcc, s20, v4
	v_ashrrev_i32_e32 v3, 31, v2
	s_nop 0
	v_addc_co_u32_e32 v7, vcc, 0, v5, vcc
	global_load_dword v40, v[6:7], off offset:2048
	v_add_co_u32_e32 v6, vcc, s26, v4
	v_lshlrev_b64 v[2:3], 11, v[2:3]
	s_nop 0
	v_addc_co_u32_e32 v7, vcc, 0, v5, vcc
	global_load_dword v41, v[6:7], off
	v_add_co_u32_e32 v6, vcc, s27, v4
	v_ashrrev_i32_e32 v1, 31, v0
	s_nop 0
	v_addc_co_u32_e32 v7, vcc, 0, v5, vcc
	global_load_dword v42, v[6:7], off offset:2048
	v_add_co_u32_e32 v6, vcc, s28, v4
	v_lshl_add_u64 v[2:3], s[90:91], 0, v[2:3]
	s_nop 0
	v_addc_co_u32_e32 v7, vcc, 0, v5, vcc
	global_load_dword v43, v[6:7], off
	v_add_co_u32_e32 v6, vcc, s29, v4
	v_lshl_add_u64 v[14:15], v[0:1], 1, v[2:3]
	s_nop 0
	v_addc_co_u32_e32 v7, vcc, 0, v5, vcc
	global_load_dword v44, v[6:7], off offset:2048
	v_add_co_u32_e32 v6, vcc, s30, v4
	s_nop 1
	v_addc_co_u32_e32 v7, vcc, 0, v5, vcc
	global_load_dword v45, v[6:7], off
	v_add_co_u32_e32 v6, vcc, s31, v4
	s_nop 1
	v_addc_co_u32_e32 v7, vcc, 0, v5, vcc
	global_load_dword v47, v[6:7], off offset:2048
	v_add_co_u32_e32 v6, vcc, s34, v4
	s_nop 1
	v_addc_co_u32_e32 v7, vcc, 0, v5, vcc
	global_load_dword v46, v[6:7], off
	v_add_co_u32_e32 v6, vcc, s35, v4
	s_nop 1
	v_addc_co_u32_e32 v7, vcc, 0, v5, vcc
; __device__ __forceinline__ void cvt_job(int& tbase, const float* __restrict__ src, int Nsrc, int K, bf16_t* __restrict__ dst, int ndst, int mode,
;                                         const float* __restrict__ gain, const float* __restrict__ up_f, const float* __restrict__ up_b, int bi, int nb) {
;     ...
;             const float* sp = src + (size_t)k0 * Nsrc + col;
; #pragma unroll
;             for (int j = 0; j < 64; ++j) v[j] = sp[(size_t)j * Nsrc];
;         }
;         bf16_t* dp = dst + (size_t)n * K + k0;
;         if (gain) {
	global_load_dword v48, v[6:7], off offset:2048
	v_add_co_u32_e32 v6, vcc, s36, v4
	s_nop 1
	v_addc_co_u32_e32 v7, vcc, 0, v5, vcc
	global_load_dword v49, v[6:7], off
	v_add_co_u32_e32 v6, vcc, s37, v4
	s_nop 1
	v_addc_co_u32_e32 v7, vcc, 0, v5, vcc
	global_load_dword v50, v[6:7], off offset:2048
	v_add_co_u32_e32 v6, vcc, s38, v4
	s_nop 1
	v_addc_co_u32_e32 v7, vcc, 0, v5, vcc
	global_load_dword v51, v[6:7], off
	v_add_co_u32_e32 v6, vcc, s39, v4
	s_nop 1
	v_addc_co_u32_e32 v7, vcc, 0, v5, vcc
	global_load_dword v52, v[6:7], off offset:2048
	v_add_co_u32_e32 v6, vcc, s40, v4
	s_nop 1
	v_addc_co_u32_e32 v7, vcc, 0, v5, vcc
	global_load_dword v53, v[6:7], off
	v_add_co_u32_e32 v6, vcc, s41, v4
	s_nop 1
	v_addc_co_u32_e32 v7, vcc, 0, v5, vcc
	global_load_dword v55, v[6:7], off offset:2048
	v_add_co_u32_e32 v6, vcc, s42, v4
	s_nop 1
	v_addc_co_u32_e32 v7, vcc, 0, v5, vcc
	global_load_dword v54, v[6:7], off
	v_add_co_u32_e32 v6, vcc, s43, v4
	s_nop 1
	v_addc_co_u32_e32 v7, vcc, 0, v5, vcc
	global_load_dword v56, v[6:7], off offset:2048
	v_add_co_u32_e32 v6, vcc, s44, v4
	s_nop 1
	v_addc_co_u32_e32 v7, vcc, 0, v5, vcc
	global_load_dword v57, v[6:7], off
	v_add_co_u32_e32 v6, vcc, s45, v4
	s_nop 1
	v_addc_co_u32_e32 v7, vcc, 0, v5, vcc
	global_load_dword v58, v[6:7], off offset:2048
	v_add_co_u32_e32 v6, vcc, s46, v4
	s_nop 1
	v_addc_co_u32_e32 v7, vcc, 0, v5, vcc
	global_load_dword v59, v[6:7], off
	v_add_co_u32_e32 v6, vcc, s47, v4
	s_nop 1
	v_addc_co_u32_e32 v7, vcc, 0, v5, vcc
	global_load_dword v60, v[6:7], off offset:2048
	v_add_co_u32_e32 v6, vcc, s48, v4
	s_nop 1
	v_addc_co_u32_e32 v7, vcc, 0, v5, vcc
	global_load_dword v61, v[6:7], off
	v_add_co_u32_e32 v6, vcc, s49, v4
	s_nop 1
	v_addc_co_u32_e32 v7, vcc, 0, v5, vcc
	global_load_dword v63, v[6:7], off offset:2048
	v_add_co_u32_e32 v6, vcc, s50, v4
	s_nop 1
	v_addc_co_u32_e32 v7, vcc, 0, v5, vcc
	global_load_dword v62, v[6:7], off
	v_add_co_u32_e32 v6, vcc, s51, v4
	s_nop 1
	v_addc_co_u32_e32 v7, vcc, 0, v5, vcc
	global_load_dword v64, v[6:7], off offset:2048
	v_add_co_u32_e32 v6, vcc, s52, v4
	s_nop 1
	v_addc_co_u32_e32 v7, vcc, 0, v5, vcc
	global_load_dword v65, v[6:7], off
	v_add_co_u32_e32 v6, vcc, s53, v4
	s_nop 1
	v_addc_co_u32_e32 v7, vcc, 0, v5, vcc
	global_load_dword v66, v[6:7], off offset:2048
	v_add_co_u32_e32 v6, vcc, s54, v4
	s_nop 1
	v_addc_co_u32_e32 v7, vcc, 0, v5, vcc
	global_load_dword v67, v[6:7], off
	v_add_co_u32_e32 v6, vcc, s55, v4
	s_nop 1
	v_addc_co_u32_e32 v7, vcc, 0, v5, vcc
	global_load_dword v68, v[6:7], off offset:2048
	v_add_co_u32_e32 v6, vcc, s56, v4
	s_nop 1
	v_addc_co_u32_e32 v7, vcc, 0, v5, vcc
	global_load_dword v69, v[6:7], off
	v_add_co_u32_e32 v6, vcc, s57, v4
	s_nop 1
	v_addc_co_u32_e32 v7, vcc, 0, v5, vcc
	global_load_dword v71, v[6:7], off offset:2048
	v_add_co_u32_e32 v6, vcc, s58, v4
	s_nop 1
	v_addc_co_u32_e32 v7, vcc, 0, v5, vcc
	global_load_dword v70, v[6:7], off
	v_add_co_u32_e32 v6, vcc, s59, v4
	s_nop 1
	v_addc_co_u32_e32 v7, vcc, 0, v5, vcc
	global_load_dword v72, v[6:7], off offset:2048
	v_add_co_u32_e32 v6, vcc, s60, v4
	s_nop 1
	v_addc_co_u32_e32 v7, vcc, 0, v5, vcc
	global_load_dword v73, v[6:7], off
	v_add_co_u32_e32 v6, vcc, s61, v4
	s_nop 1
	v_addc_co_u32_e32 v7, vcc, 0, v5, vcc
	global_load_dword v74, v[6:7], off offset:2048
	v_add_co_u32_e32 v6, vcc, s62, v4
	s_nop 1
	v_addc_co_u32_e32 v7, vcc, 0, v5, vcc
	global_load_dword v75, v[6:7], off
	v_add_co_u32_e32 v6, vcc, s63, v4
	s_nop 1
	v_addc_co_u32_e32 v7, vcc, 0, v5, vcc
	global_load_dword v76, v[6:7], off offset:2048
	v_add_co_u32_e32 v6, vcc, 0x155000, v4
	s_nop 1
	v_addc_co_u32_e32 v7, vcc, 0, v5, vcc
	v_add_co_u32_e32 v4, vcc, 0x15a000, v4
	global_load_dword v77, v[6:7], off
	s_nop 0
	v_addc_co_u32_e32 v5, vcc, 0, v5, vcc
	global_load_dword v78, v[4:5], off offset:2048
	s_and_b64 vcc, exec, s[2:3]
	s_cbranch_vccz .LBB0_27
; __device__ __forceinline__ unsigned cvt_pk_bf16(float lo, float hi) { unsigned r; asm volatile("v_cvt_pk_bf16_f32 %0, %1, %2" : "=v"(r) : "v"(lo), "v"(hi)); return r; }
; __device__ __forceinline__ void cvt_job(int& tbase, const float* __restrict__ src, int Nsrc, int K, bf16_t* __restrict__ dst, int ndst, int mode,
;                                         const float* __restrict__ gain, const float* __restrict__ up_f, const float* __restrict__ up_b, int bi, int nb) {
;     ...
;         if (gain) {
; #pragma unroll
;             for (int j8 = 0; j8 < 8; ++j8) { const f32x4 g0 = *(const f32x4*)(gain + k0 + 8 * j8), g1 = *(const f32x4*)(gain + k0 + 8 * j8 + 4);
;                 u32x4 w; w.x = cvt_pk_bf16(v[8 * j8] * g0[0] * scale, v[8 * j8 + 1] * g0[1] * scale); w.y = cvt_pk_bf16(v[8 * j8 + 2] * g0[2] * scale, v[8 * j8 + 3] * g0[3] * scale);
;                 w.z = cvt_pk_bf16(v[8 * j8 + 4] * g1[0] * scale, v[8 * j8 + 5] * g1[1] * scale); w.w = cvt_pk_bf16(v[8 * j8 + 6] * g1[2] * scale, v[8 * j8 + 7] * g1[3] * scale);
;                 *(u32x4*)(dp + 8 * j8) = w; }
	v_lshl_add_u64 v[80:81], v[0:1], 2, s[6:7]
	global_load_dwordx4 v[84:87], v[80:81], off
	global_load_dwordx4 v[88:91], v[80:81], off offset:16
	global_load_dwordx4 v[92:95], v[80:81], off offset:32
	global_load_dwordx4 v[96:99], v[80:81], off offset:48
	global_load_dwordx4 v[100:103], v[80:81], off offset:64
	global_load_dwordx4 v[104:107], v[80:81], off offset:80
	global_load_dwordx4 v[108:111], v[80:81], off offset:96
	global_load_dwordx4 v[112:115], v[80:81], off offset:112
	global_load_dwordx4 v[116:119], v[80:81], off offset:128
	global_load_dwordx4 v[120:123], v[80:81], off offset:144
	global_load_dwordx4 v[124:127], v[80:81], off offset:160
	global_load_dwordx4 v[128:131], v[80:81], off offset:176
	global_load_dwordx4 v[132:135], v[80:81], off offset:192
	global_load_dwordx4 v[136:139], v[80:81], off offset:208
	global_load_dwordx4 v[140:143], v[80:81], off offset:224
	global_load_dwordx4 v[144:147], v[80:81], off offset:240
	s_waitcnt vmcnt(0)
	s_nop 1
	v_mov_b32_e32 v0, v84
	v_mov_b32_e32 v1, v85
	v_mov_b32_e32 v2, v86
	v_mov_b32_e32 v3, v87
	s_nop 1
	v_mov_b32_e32 v4, v88
	v_mov_b32_e32 v5, v89
	v_mov_b32_e32 v6, v90
	v_mov_b32_e32 v7, v91
	v_mul_f32_e32 v0, v11, v0
	v_mul_f32_e32 v1, v16, v1
	v_mul_f32_e32 v2, v17, v2
	v_mul_f32_e32 v3, v18, v3
	v_mul_f32_e32 v4, v19, v4
	v_mul_f32_e32 v5, v20, v5
	v_mul_f32_e32 v6, v21, v6
	v_mul_f32_e32 v7, v23, v7
	v_cvt_pk_bf16_f32 v0, v0, v1
	v_cvt_pk_bf16_f32 v1, v2, v3
	v_cvt_pk_bf16_f32 v2, v4, v5
	v_cvt_pk_bf16_f32 v3, v6, v7
	global_store_dwordx4 v[14:15], v[0:3], off
	s_nop 1
	v_mov_b32_e32 v0, v92
	v_mov_b32_e32 v1, v93
	v_mov_b32_e32 v2, v94
	v_mov_b32_e32 v3, v95
	s_nop 0
	s_nop 1
	v_mov_b32_e32 v4, v96
	v_mov_b32_e32 v5, v97
	v_mov_b32_e32 v6, v98
	v_mov_b32_e32 v7, v99
	v_mul_f32_e32 v0, v22, v0
	v_mul_f32_e32 v1, v24, v1
	v_mul_f32_e32 v2, v25, v2
	v_mul_f32_e32 v3, v26, v3
	v_mul_f32_e32 v4, v27, v4
	v_mul_f32_e32 v5, v28, v5
	v_mul_f32_e32 v6, v29, v6
	v_mul_f32_e32 v7, v31, v7
	v_cvt_pk_bf16_f32 v0, v0, v1
	v_cvt_pk_bf16_f32 v1, v2, v3
	v_cvt_pk_bf16_f32 v2, v4, v5
	v_cvt_pk_bf16_f32 v3, v6, v7
	global_store_dwordx4 v[14:15], v[0:3], off offset:16
	s_nop 1
	v_mov_b32_e32 v0, v100
	v_mov_b32_e32 v1, v101
	v_mov_b32_e32 v2, v102
	v_mov_b32_e32 v3, v103
	s_nop 0
	s_nop 1
	v_mov_b32_e32 v4, v104
	v_mov_b32_e32 v5, v105
	v_mov_b32_e32 v6, v106
	v_mov_b32_e32 v7, v107
	v_mul_f32_e32 v0, v30, v0
	v_mul_f32_e32 v1, v32, v1
	v_mul_f32_e32 v2, v33, v2
	v_mul_f32_e32 v3, v34, v3
	v_mul_f32_e32 v4, v35, v4
	v_mul_f32_e32 v5, v36, v5
	v_mul_f32_e32 v6, v37, v6
	v_mul_f32_e32 v7, v39, v7
	v_cvt_pk_bf16_f32 v0, v0, v1
	v_cvt_pk_bf16_f32 v1, v2, v3
	v_cvt_pk_bf16_f32 v2, v4, v5
	v_cvt_pk_bf16_f32 v3, v6, v7
	global_store_dwordx4 v[14:15], v[0:3], off offset:32
	s_nop 1
	v_mov_b32_e32 v0, v108
	v_mov_b32_e32 v1, v109
	v_mov_b32_e32 v2, v110
	v_mov_b32_e32 v3, v111
	s_nop 0
	s_nop 1
	v_mov_b32_e32 v4, v112
	v_mov_b32_e32 v5, v113
	v_mov_b32_e32 v6, v114
	v_mov_b32_e32 v7, v115
	v_mul_f32_e32 v0, v38, v0
	v_mul_f32_e32 v1, v40, v1
	v_mul_f32_e32 v2, v41, v2
	v_mul_f32_e32 v3, v42, v3
	v_mul_f32_e32 v4, v43, v4
	v_mul_f32_e32 v5, v44, v5
	v_mul_f32_e32 v6, v45, v6
	v_mul_f32_e32 v7, v47, v7
	v_cvt_pk_bf16_f32 v0, v0, v1
	v_cvt_pk_bf16_f32 v1, v2, v3
	v_cvt_pk_bf16_f32 v2, v4, v5
	v_cvt_pk_bf16_f32 v3, v6, v7
	global_store_dwordx4 v[14:15], v[0:3], off offset:48
	s_nop 1
	v_mov_b32_e32 v0, v116
	v_mov_b32_e32 v1, v117
	v_mov_b32_e32 v2, v118
	v_mov_b32_e32 v3, v119
	s_nop 0
	s_nop 1
	v_mov_b32_e32 v4, v120
	v_mov_b32_e32 v5, v121
	v_mov_b32_e32 v6, v122
	v_mov_b32_e32 v7, v123
	v_mul_f32_e32 v0, v46, v0
	v_mul_f32_e32 v1, v48, v1
	v_mul_f32_e32 v2, v49, v2
	v_mul_f32_e32 v3, v50, v3
	v_mul_f32_e32 v4, v51, v4
	v_mul_f32_e32 v5, v52, v5
	v_mul_f32_e32 v6, v53, v6
	v_mul_f32_e32 v7, v55, v7
	v_cvt_pk_bf16_f32 v0, v0, v1
	v_cvt_pk_bf16_f32 v1, v2, v3
	v_cvt_pk_bf16_f32 v2, v4, v5
	v_cvt_pk_bf16_f32 v3, v6, v7
	global_store_dwordx4 v[14:15], v[0:3], off offset:64
	s_nop 1
	v_mov_b32_e32 v0, v124
	v_mov_b32_e32 v1, v125
	v_mov_b32_e32 v2, v126
	v_mov_b32_e32 v3, v127
	s_nop 0
	s_nop 1
	v_mov_b32_e32 v4, v128
	v_mov_b32_e32 v5, v129
	v_mov_b32_e32 v6, v130
	v_mov_b32_e32 v7, v131
	v_mul_f32_e32 v0, v54, v0
	v_mul_f32_e32 v1, v56, v1
	v_mul_f32_e32 v2, v57, v2
	v_mul_f32_e32 v3, v58, v3
	v_mul_f32_e32 v4, v59, v4
	v_mul_f32_e32 v5, v60, v5
	v_mul_f32_e32 v6, v61, v6
	v_mul_f32_e32 v7, v63, v7
	v_cvt_pk_bf16_f32 v0, v0, v1
	v_cvt_pk_bf16_f32 v1, v2, v3
	v_cvt_pk_bf16_f32 v2, v4, v5
	v_cvt_pk_bf16_f32 v3, v6, v7
	global_store_dwordx4 v[14:15], v[0:3], off offset:80
	s_nop 1
	v_mov_b32_e32 v0, v132
	v_mov_b32_e32 v1, v133
	v_mov_b32_e32 v2, v134
	v_mov_b32_e32 v3, v135
	s_nop 0
	s_nop 1
	v_mov_b32_e32 v4, v136
	v_mov_b32_e32 v5, v137
	v_mov_b32_e32 v6, v138
	v_mov_b32_e32 v7, v139
	v_mul_f32_e32 v0, v62, v0
	v_mul_f32_e32 v1, v64, v1
	v_mul_f32_e32 v2, v65, v2
	v_mul_f32_e32 v3, v66, v3
	v_mul_f32_e32 v4, v67, v4
	v_mul_f32_e32 v5, v68, v5
	v_mul_f32_e32 v6, v69, v6
	v_mul_f32_e32 v7, v71, v7
	v_cvt_pk_bf16_f32 v0, v0, v1
	v_cvt_pk_bf16_f32 v1, v2, v3
	v_cvt_pk_bf16_f32 v2, v4, v5
	v_cvt_pk_bf16_f32 v3, v6, v7
	s_nop 1
	v_mov_b32_e32 v4, v140
	v_mov_b32_e32 v5, v141
	v_mov_b32_e32 v6, v142
	v_mov_b32_e32 v7, v143
	s_nop 0
	s_nop 1
	v_mov_b32_e32 v80, v144
	v_mov_b32_e32 v81, v145
	v_mov_b32_e32 v82, v146
	v_mov_b32_e32 v83, v147
	v_mul_f32_e32 v4, v70, v4
	v_mul_f32_e32 v5, v72, v5
	v_mul_f32_e32 v6, v73, v6
	v_mul_f32_e32 v7, v74, v7
	v_mul_f32_e32 v79, v75, v80
	v_mul_f32_e32 v80, v76, v81
	v_mul_f32_e32 v81, v77, v82
	v_mul_f32_e32 v82, v78, v83
	v_cvt_pk_bf16_f32 v4, v4, v5
	v_cvt_pk_bf16_f32 v5, v6, v7
	v_cvt_pk_bf16_f32 v6, v79, v80
	v_cvt_pk_bf16_f32 v7, v81, v82
	s_cbranch_execnz .LBB0_24
	s_branch .LBB0_28
